# P2a: next-layer filter-tap / weight-conversion items run before the attention units
# speedup vs baseline: 1.0057x; 1.0004x over previous
; #define LAS __attribute__((address_space(3)))
; __device__ __forceinline__ void attn_mfma(LAS unsigned char* lds, int layer, int G, const int wave_s) {
;     ...
;     const bf16_t* Q = (const bf16_t*)(ws + WS_Q); const bf16_t* Kb = (const bf16_t*)(ws + WS_K); const bf16_t* Vb = (const bf16_t*)(ws + WS_V);
;     bf16_t* YM = (bf16_t*)(ws + WS_YM); const float* ZT = (const float*)(ws + WS_SSHY);
;     const float* gat = Pp->in[20] + layer * ATTW; const float* ghy = Pp->in[19] + layer * HY;
;     const int r32 = lane & 31, hi = lane >> 5, h = wave, kv = h >> 2;
;     const float sk = Pp->in[18][layer * NH + h] * LOG2E;
;     const unsigned lbase = (unsigned)(uintptr_t)lds;
;     LAS float* al_l = (LAS float*)(lds + AT_SCR) + wave * 64; LAS float* li_l = al_l + 32;
;     LAS float* xa = (LAS float*)(lds + AT_XA); LAS float* xh = (LAS float*)(lds + AT_XH);
;     const int nunits = layer == DEPTH - 1 ? ML / 32 : MT / 32;
;     for (int unit = blockIdx.x; unit < nunits; unit += G) {
; __global__ void __launch_bounds__(NTHR, 2) mk_fwd(Params P) {
;     ...
;             attn_mfma(lds, layer, G, wave_s);
;             if (layer + 1 < DEPTH && (int)blockIdx.x >= MC / 32) { __syncthreads();
;                 taps_items<4>(layer + 1, 1, ((int)blockIdx.x - MC / 32) * NWAVES + wave_s, (G - MC / 32) * NWAVES, wave_s); }
.LBB0_785:
	s_andn2_b64 vcc, exec, s[36:37]
	s_cbranch_vccnz .LBB0_884
	s_mov_b32 s98, 0
	s_cmp_lg_u32 s76, 3
	s_cselect_b64 s[44:45], -1, 0
	s_branch .LBB0_826
.Lp2a_attn:
	s_cmp_lg_u32 s76, 3
	s_cselect_b64 s[44:45], -1, 0
	s_and_b64 s[0:1], s[44:45], exec
	s_movk_i32 s0, 0x110
	s_cselect_b32 s0, s0, 0x100
	s_cmp_ge_i32 s2, s0
	v_readlane_b32 s17, v253, 2
	s_mov_b64 s[36:37], s[94:95]
	v_mbcnt_lo_u32_b32 v0, -1, 0
	v_mbcnt_hi_u32_b32 v0, -1, v0
	s_cbranch_scc1 .LBB0_826
	s_load_dwordx2 s[40:41], s[36:37], 0xd8
	s_lshl_b32 s10, s76, 3
	s_lshl_b32 s1, s17, 6
	v_and_b32_e32 v184, 31, v0
	s_waitcnt vmcnt(0)
	v_lshlrev_b32_e32 v4, 4, v0
	s_waitcnt lgkmcnt(0)
	s_add_u32 s46, s40, 0xac20000
	s_addc_u32 s47, s41, 0
	s_add_u32 s48, s40, 0xb060000
	s_addc_u32 s49, s41, 0
	s_add_u32 s42, s40, 0xb4a0000
	s_addc_u32 s43, s41, 0
	s_add_i32 s10, s17, s10
	s_ashr_i32 s11, s10, 31
	s_lshl_b64 s[38:39], s[10:11], 2
	s_load_dwordx2 s[10:11], s[36:37], 0x90
	s_load_dwordx4 s[52:55], s[36:37], 0x98
	v_and_b32_e32 v6, 0xc0, v4
	v_lshlrev_b32_e32 v7, 1, v0
	v_and_b32_e32 v7, 32, v7
	s_waitcnt lgkmcnt(0)
	s_add_u32 s10, s10, s38
	s_addc_u32 s11, s11, s39
	global_load_dword v2, v1, s[10:11]
	s_lshl_b32 s10, s17, 8
	s_add_i32 s15, s10, 0
	s_lshl_b32 s26, s76, 10
	s_add_i32 s15, s15, 0x20000
	s_lshl_b64 s[10:11], s[26:27], 2
	s_add_u32 s56, s52, s10
	s_addc_u32 s57, s53, s11
	s_add_u32 s54, s54, s10
	s_addc_u32 s55, s55, s11
	s_lshl_b32 s60, s17, 7
	s_ashr_i32 s61, s60, 31
	s_lshl_b64 s[52:53], s[60:61], 1
	s_add_u32 s10, s40, s52
	s_addc_u32 s11, s41, s53
	s_add_u32 s50, s10, 0x9b20000
	s_addc_u32 s51, s11, 0
	s_lshl_b32 s10, s17, 12
	s_and_b32 s10, s10, 0xffffc000
	s_add_i32 s11, s10, 0
	v_lshl_add_u32 v188, v184, 8, s11
	s_add_i32 s11, 0, 0x8000
	v_add_u32_e32 v6, s11, v6
	v_ashrrev_i32_e32 v185, 5, v0
	v_mov_b32_e32 v163, v1
	s_mulk_i32 s17, 0x2200
	v_lshlrev_b32_e32 v187, 4, v185
	v_cmp_gt_u32_e64 s[36:37], 32, v0
	s_mov_b64 s[28:29], 0xd6a0000
	s_add_i32 s17, s17, 0
	v_ashrrev_i32_e32 v194, 4, v0
	v_lshl_add_u32 v193, v184, 1, s17
	v_lshlrev_b32_e32 v189, 2, v185
	v_lshlrev_b32_e32 v5, 2, v184
	v_readlane_b32 s23, v255, 7
	s_add_i32 s11, s60, 0
	s_add_i32 s11, s11, 0x20c00
	v_add_u32_e32 v190, s15, v5
	v_add_u32_e32 v209, s15, v187
	s_movk_i32 s15, 0x440
	v_cmp_eq_u32_e64 s[38:39], 0, v184
	s_waitcnt vmcnt(0)
	v_mul_f32_e32 v186, 0x3fb8aa3b, v2
	v_lshlrev_b32_e32 v2, 3, v0
	v_and_b32_e32 v3, 24, v2
	v_and_b32_e32 v2, 0x100, v2
	v_add3_u32 v3, v6, v3, v7
	v_add3_u32 v191, v3, v2, s10
	v_and_b32_e32 v2, 7, v0
	v_lshlrev_b32_e32 v162, 4, v2
	v_and_b32_e32 v6, -8, v0
	v_lshlrev_b32_e32 v192, 2, v2
	v_lshl_add_u64 v[2:3], s[40:41], 0, v[162:163]
	v_cmp_gt_i32_e64 s[40:41], 8, v0
	v_and_b32_e32 v0, 0xf0, v4
	v_lshl_add_u64 v[164:165], v[2:3], 0, s[28:29]
	v_add_u32_e32 v196, s17, v0
	s_movk_i32 s17, 0x70
	v_add_u32_e32 v3, 32, v187
	v_bitop3_b32 v202, v3, v4, s17 bitop3:0x78
	v_add_u32_e32 v3, 64, v187
	v_bitop3_b32 v203, v3, v4, s17 bitop3:0x78
	v_add_u32_e32 v3, 0x60, v187
	v_bitop3_b32 v204, v3, v4, s17 bitop3:0x78
	v_add_u32_e32 v3, 0x80, v187
	v_bitop3_b32 v205, v3, v4, s17 bitop3:0x78
	v_add_u32_e32 v3, 0xa0, v187
	v_bitop3_b32 v206, v3, v4, s17 bitop3:0x78
	v_add_u32_e32 v3, 0xc0, v187
	v_bitop3_b32 v207, v3, v4, s17 bitop3:0x78
	v_add_u32_e32 v3, 0xe0, v187
	v_or_b32_e32 v2, s60, v184
	v_bitop3_b32 v200, v187, v4, s17 bitop3:0x78
	v_bitop3_b32 v208, v3, v4, s17 bitop3:0x78
	v_add_u32_e32 v4, s1, v6
	s_mov_b32 s17, 0x8800
	v_add_u32_e32 v6, 0x200, v4
	v_ashrrev_i32_e32 v3, 31, v2
	s_add_i32 s10, s23, s60
	v_add_u32_e32 v163, s23, v5
	s_movk_i32 s23, 0x110
	v_mad_i64_i32 v[166:167], s[28:29], v4, s17, 0
	v_mad_i64_i32 v[168:169], s[28:29], v6, s17, 0
	v_lshl_add_u64 v[180:181], v[2:3], 2, s[54:55]
	v_or_b32_e32 v3, 1, v189
	v_mul_lo_u32 v198, v194, s23
	v_ashrrev_i32_e32 v5, 31, v4
	v_mul_lo_u32 v210, v3, s23
	s_add_u32 s28, s42, s52
	v_ashrrev_i32_e32 v7, 31, v6
	v_lshl_add_u64 v[174:175], v[4:5], 2, s[56:57]
	v_lshl_add_u64 v[176:177], v[4:5], 1, s[42:43]
	v_mul_lo_u32 v2, v185, s15
	v_add_u32_e32 v3, 0x990, v210
	v_add_u32_e32 v4, 0x440, v198
	s_addc_u32 s29, s43, s53
	v_lshl_add_u64 v[178:179], v[6:7], 1, s[42:43]
	v_lshl_add_u64 v[182:183], s[28:29], 0, v[0:1]
	v_add_u32_e32 v211, v193, v2
	v_add_u32_e32 v212, v193, v3
	v_add_u32_e32 v213, v196, v4
	v_mbcnt_lo_u32_b32 v66, -1, 0
	v_mbcnt_hi_u32_b32 v66, -1, v66
	v_add_u32_e32 v67, s1, v66
	v_ashrrev_i32_e32 v68, 4, v67
	v_and_b32_e32 v70, 0xfffff0, v68
	v_lshlrev_b32_e32 v71, 1, v68
	v_lshlrev_b32_e32 v66, 3, v66
	v_and_or_b32 v70, v71, 8, v70
	v_and_b32_e32 v69, 0x78, v66
	v_lshrrev_b32_e32 v70, 1, v70
	v_bfe_u32 v66, v66, 5, 2
	v_lshrrev_b32_e32 v71, 1, v68
	v_or_b32_e32 v66, v70, v66
	v_and_b32_e32 v70, 3, v68
	v_lshlrev_b32_e32 v69, 1, v69
	v_and_or_b32 v70, v71, 4, v70
	v_and_b32_e32 v71, 48, v69
	v_lshlrev_b32_e32 v68, 8, v68
	v_and_b32_e32 v67, 0x70, v67
	v_lshl_or_b32 v70, v70, 6, v71
	v_bitop3_b32 v67, v69, v68, v67 bitop3:0xde
	v_lshl_or_b32 v66, v66, 9, v70
	v_mov_b32_e32 v233, v67
	v_mov_b32_e32 v234, v66
	v_mbcnt_lo_u32_b32 v236, -1, 0
	v_mbcnt_hi_u32_b32 v236, -1, v236
	v_add_u32_e32 v235, s1, v236
	v_ashrrev_i32_e32 v235, 4, v235
	v_lshlrev_b32_e32 v236, 4, v236
	v_and_b32_e32 v236, 0xf0, v236
	s_mov_b32 s15, s2
	s_cmpk_lg_u32 s3, 0x100
	s_cbranch_scc1 .Lcf_e
	s_add_i32 s15, s2, s3
	s_cmp_lt_i32 s15, s0
	s_cselect_b32 s15, s15, s2

; #define REP(k) _Pragma("unroll") for (int rep_ = 0; rep_ < (MK_REP == (k) ? 2 : 1); ++rep_)
; __global__ void __launch_bounds__(NTHR, 2) mk_fwd(Params P) {
;     ...
;         if (IN(pb + 2)) REP(3) {
;             attn_mfma(lds, layer, G, wave_s);
;             if (layer + 1 < DEPTH && (int)blockIdx.x >= MC / 32) { __syncthreads();
;                 taps_items<4>(layer + 1, 1, ((int)blockIdx.x - MC / 32) * NWAVES + wave_s, (G - MC / 32) * NWAVES, wave_s); }
;         }
.LBB0_826:
	s_cmp_eq_u32 s98, 1
	s_cbranch_scc0 .Lp2a_taps
	s_waitcnt vmcnt(0) lgkmcnt(0)
	s_barrier
	s_branch .Lp2a_end

; #define REP(k) _Pragma("unroll") for (int rep_ = 0; rep_ < (MK_REP == (k) ? 2 : 1); ++rep_)
; __global__ void __launch_bounds__(NTHR, 2) mk_fwd(Params P) {
;     ...
;         if (IN(pb + 2)) REP(3) {
;             attn_mfma(lds, layer, G, wave_s);
;             if (layer + 1 < DEPTH && (int)blockIdx.x >= MC / 32) { __syncthreads();
;                 taps_items<4>(layer + 1, 1, ((int)blockIdx.x - MC / 32) * NWAVES + wave_s, (G - MC / 32) * NWAVES, wave_s); }
;         }
.LBB0_830:
	s_cmp_eq_u32 s98, 0
	s_cbranch_scc0 .Lp2a_end
	s_mov_b32 s98, 1
	s_branch .Lp2a_attn
